# top-256 threshold search: regula falsi on log2(count) instead of count; dilated phase 11: item top waits for all but the last 4 output stores
# speedup vs baseline: 1.0014x; 1.0014x over previous
; DI int wave_sum_i(int x) { x = row_sum16(x); return __builtin_amdgcn_readlane(x, 0) + __builtin_amdgcn_readlane(x, 16) + __builtin_amdgcn_readlane(x, 32) + __builtin_amdgcn_readlane(x, 48); }
; DI void index_unit(Frame& F, int b, int t0) {
;     ...
;         unsigned res = 0u;
;         const int nreg = (t >> 6) + 1;
; #pragma unroll 1
;     ...
;             const unsigned cand = res | (1u << bit);
;             int cl = 0;
; #pragma unroll
;             for (int gq = 0; gq < 8; ++gq) if (8 * gq < nreg) {
; #pragma unroll
;                 for (int i = 8 * gq; i < 8 * gq + 8; i += 4) cl = cnt4_ge(key[i], key[i + 1], key[i + 2], key[i + 3], cand, cl); }
;             const int cnt = wave_sum_i(cl);
;             if (cnt >= 256) { res = cand; if (cnt == 256) break; }
;         }
.Lsel_decide:
	s_add_i32 s101, s101, 1
	s_cmpk_eq_i32 s35, 0x100
	s_cbranch_scc1 .Lsel_found
	s_cmpk_gt_i32 s101, 48
	s_cbranch_scc1 .Lsel_fallback0
	s_cmp_eq_u32 s99, 1
	s_cbranch_scc0 .Lsel_step
	s_cmpk_lt_i32 s35, 0x100
	s_cbranch_scc1 .Lsel_fallback
	s_mov_b32 s99, 2
	v_bfrev_b32_e32 v208, 1
	v_add_u32_e32 v209, 1, v213
	v_cvt_f32_i32_e32 v210, s35
	v_max_f32_e32 v210, 0.5, v210
	v_log_f32_e32 v210, v210
	s_nop 0
	v_add_f32_e32 v210, 0xc1000000, v210
	v_mov_b32_e32 v211, 0xc1100000
	v_mov_b32_e32 v212, 0
	s_branch .Lsel_next
.Lsel_step:
	v_cvt_f32_i32_e32 v214, s35
	v_max_f32_e32 v214, 0.5, v214
	v_log_f32_e32 v214, v214
	s_nop 0
	v_add_f32_e32 v214, 0xc1000000, v214
	s_cmpk_gt_i32 s35, 0x100
	s_cbranch_scc0 .Lsel_below
	v_mov_b32_e32 v208, v5
	v_mov_b32_e32 v210, v214
	v_cmp_eq_u32_e64 s[44:45], 1, v212
	v_mul_f32_e32 v215, 0.5, v211
	s_nop 1
	v_cndmask_b32_e64 v211, v211, v215, s[44:45]
	v_mov_b32_e32 v212, 1
	s_branch .Lsel_next

; DI void dil_unit(Frame& F, const DilItem& it, bool has_next, const DilItem& nx, RowRegs<128>& RK, RowRegs<128>& RV) {
;     ...
;     __syncthreads();
;     { const float* bd = (const float*)(F.ws + WS_BIASDIL) + (g * 16 + h) * 160;
;       if (F.tid <= 128) tb[128 - F.tid] = bd[F.tid]; }
.Lqp11_fast0:
	s_waitcnt vmcnt(4)
	s_barrier

; DI void dil_unit(Frame& F, const DilItem& it, bool has_next, const DilItem& nx, RowRegs<128>& RK, RowRegs<128>& RV) {
;     ...
;     __syncthreads();
;     { const float* bd = (const float*)(F.ws + WS_BIASDIL) + (g * 16 + h) * 160;
;       if (F.tid <= 128) tb[128 - F.tid] = bd[F.tid]; }
.LBB0_1177:
	s_bfe_u32 s98, s5, 0x40004
	s_mulk_i32 s98, 0x280
	v_writelane_b32 v229, s98, 56
	s_bfe_u32 s55, s19, 0x40004
	v_readlane_b32 s98, v229, 58
	s_nop 0
	s_cmp_lg_u32 s98, 0
	s_cbranch_scc1 .Lqp11_fast0
	s_waitcnt vmcnt(0)
	s_barrier
	s_and_saveexec_b64 s[28:29], s[0:1]
	s_cbranch_execz .LBB0_1179
	s_mul_i32 s8, s55, 0x280
	v_lshl_add_u64 v[0:1], v[150:151], 0, s[8:9]
	global_load_dword v0, v[0:1], off
	s_waitcnt vmcnt(0)
	ds_write_b32 v145, v0
